# final_norm: g vector hoisted out of the row loop, row stores no longer serialized behind per-quad g loads
# speedup vs baseline: 1.1054x; 1.0036x over previous
; #define TIDX ((wv_ << 6) | lane_id_l())
; #define p (kparams())
; __device__ __forceinline__ void final_norm(const int wv_, KPR p) {
;   const int wid = TIDX >> 6, lane = TIDX & 63;
;   const float* gvec = p->in[I_GFIN];
;   for (int row = blockIdx.x * 8 + wid; row < NB * SEQ; row += gridDim.x * 8) {
;     float* x = p->out + (size_t)row * D;
;     f32x4 v[8]; float ss = 0.f;
; #pragma unroll
;     for (int j = 0; j < 8; ++j) { v[j] = *(const f32x4*)(x + lane * 4 + 256 * j); ss += v[j][0] * v[j][0] + v[j][1] * v[j][1] + v[j][2] * v[j][2] + v[j][3] * v[j][3]; }
;     const float rstd = rsqrtf(wave_sum(ss) * (1.f / D) + 1e-6f);
; #pragma unroll
;     for (int j = 0; j < 8; ++j) { const int c = lane * 4 + 256 * j; const f32x4 g = *(const f32x4*)(gvec + c);
;       *(f32x4*)(x + c) = v[j] * rstd * g; }
;   }
; }
.LBB0_1365:
	v_mov_b32_e32 v0, v153
	v_readlane_b32 s2, v242, 2
	v_or_b32_e32 v0, s77, v0
	v_ashrrev_i32_e32 v0, 6, v0
	v_add_u32_e32 v4, s2, v0
	s_movk_i32 s2, 0x4000
	v_cmp_gt_i32_e32 vcc, s2, v4
	s_and_saveexec_b64 s[2:3], vcc
	s_cbranch_execz .LBB0_1368
	s_load_dwordx2 s[4:5], s[0:1], 0x40
	s_load_dwordx2 s[2:3], s[0:1], 0x110
	v_lshlrev_b32_e32 v0, 2, v153
	v_and_b32_e32 v0, 0xfc, v0
	v_mov_b32_e32 v7, 0
	v_lshlrev_b32_e32 v6, 2, v0
	v_or_b32_e32 v2, 0x400, v0
	s_waitcnt lgkmcnt(0)
	v_lshl_add_u64 v[8:9], s[4:5], 0, v[6:7]
	v_lshlrev_b32_e32 v6, 2, v2
	v_or_b32_e32 v20, 0x500, v0
	v_lshl_add_u64 v[10:11], s[4:5], 0, v[6:7]
	v_lshlrev_b32_e32 v6, 2, v20
	v_or_b32_e32 v22, 0x600, v0
	v_lshl_add_u64 v[12:13], s[4:5], 0, v[6:7]
	v_lshlrev_b32_e32 v6, 2, v22
	v_or_b32_e32 v24, 0x700, v0
	v_lshl_add_u64 v[14:15], s[4:5], 0, v[6:7]
	v_lshlrev_b32_e32 v6, 2, v24
	v_lshl_add_u64 v[16:17], s[4:5], 0, v[6:7]
	s_mov_b64 s[0:1], 0
	v_lshlrev_b32_e32 v6, 2, v0
	s_movk_i32 s4, 0x1000
	v_mov_b32_e32 v30, 0x358637bd
	s_mov_b32 s5, 0x800000
	v_lshlrev_b32_e32 v18, 2, v2
	v_mov_b32_e32 v19, v7
	v_lshlrev_b32_e32 v20, 2, v20
	v_mov_b32_e32 v21, v7
	v_lshlrev_b32_e32 v22, 2, v22
	v_mov_b32_e32 v23, v7
	v_lshlrev_b32_e32 v24, 2, v24
	v_mov_b32_e32 v25, v7
	s_movk_i32 s6, 0x3fff
	global_load_dwordx4 v[88:91], v[8:9], off
	global_load_dwordx4 v[92:95], v[8:9], off offset:1024
	global_load_dwordx4 v[96:99], v[8:9], off offset:2048
	global_load_dwordx4 v[100:103], v[8:9], off offset:3072
	global_load_dwordx4 v[104:107], v[10:11], off
	global_load_dwordx4 v[108:111], v[12:13], off
	global_load_dwordx4 v[112:115], v[14:15], off
	global_load_dwordx4 v[116:119], v[16:17], off
.LBB0_1367:
	v_ashrrev_i32_e32 v5, 31, v4
	v_lshlrev_b64 v[0:1], 13, v[4:5]
	v_lshl_add_u64 v[26:27], s[2:3], 0, v[0:1]
	v_lshl_add_u64 v[28:29], v[26:27], 0, v[6:7]
	v_add_co_u32_e32 v64, vcc, s4, v28
	v_add_u32_e32 v4, s73, v4
	s_nop 0
	v_addc_co_u32_e32 v65, vcc, 0, v29, vcc
	global_load_dwordx4 v[32:35], v[28:29], off
	global_load_dwordx4 v[36:39], v[28:29], off offset:1024
	global_load_dwordx4 v[40:43], v[28:29], off offset:2048
	global_load_dwordx4 v[44:47], v[28:29], off offset:3072
	global_load_dwordx4 v[48:51], v[64:65], off
	global_load_dwordx4 v[52:55], v[64:65], off offset:1024
	global_load_dwordx4 v[56:59], v[64:65], off offset:2048
	global_load_dwordx4 v[0:3], v[64:65], off offset:3072
	s_waitcnt vmcnt(7)
	v_mul_f32_e32 v5, v33, v33
	s_waitcnt vmcnt(6)
	v_mul_f32_e32 v31, v37, v37
	s_waitcnt vmcnt(5)
	v_mul_f32_e32 v80, v41, v41
	v_fmac_f32_e32 v5, v32, v32
	v_fmac_f32_e32 v31, v36, v36
	s_waitcnt vmcnt(4)
	v_mul_f32_e32 v81, v45, v45
	s_waitcnt vmcnt(3)
	v_mov_b32_e32 v66, v49
	s_waitcnt vmcnt(2)
	v_mov_b32_e32 v67, v53
	v_fmac_f32_e32 v80, v40, v40
	v_fmac_f32_e32 v5, v34, v34
	v_fmac_f32_e32 v31, v38, v38
	v_mov_b32_e32 v64, v48
	v_mov_b32_e32 v65, v52
	v_fmac_f32_e32 v81, v44, v44
	v_pk_mul_f32 v[66:67], v[66:67], v[66:67]
	v_fmac_f32_e32 v80, v42, v42
	v_fmac_f32_e32 v5, v35, v35
	v_fmac_f32_e32 v31, v39, v39
	s_waitcnt vmcnt(1)
	v_mov_b32_e32 v70, v57
	s_waitcnt vmcnt(0)
	v_mov_b32_e32 v71, v1
	v_mov_b32_e32 v72, v50
	v_mov_b32_e32 v73, v54
	v_fmac_f32_e32 v81, v46, v46
	v_pk_fma_f32 v[64:65], v[64:65], v[64:65], v[66:67]
	v_fmac_f32_e32 v80, v43, v43
	v_add_f32_e32 v5, v5, v31
	v_mov_b32_e32 v68, v56
	v_mov_b32_e32 v69, v0
	v_mov_b32_e32 v76, v51
	v_mov_b32_e32 v77, v55
	v_pk_mul_f32 v[70:71], v[70:71], v[70:71]
	v_fmac_f32_e32 v81, v47, v47
	v_pk_fma_f32 v[64:65], v[72:73], v[72:73], v[64:65]
	v_add_f32_e32 v5, v5, v80
	v_mov_b32_e32 v74, v58
	v_mov_b32_e32 v75, v2
	v_pk_fma_f32 v[66:67], v[68:69], v[68:69], v[70:71]
	v_pk_fma_f32 v[64:65], v[76:77], v[76:77], v[64:65]
	v_add_f32_e32 v5, v5, v81
	v_mov_b32_e32 v78, v59
	v_mov_b32_e32 v79, v3
	v_pk_fma_f32 v[66:67], v[74:75], v[74:75], v[66:67]
	v_add_f32_e32 v5, v5, v64
	v_pk_fma_f32 v[66:67], v[78:79], v[78:79], v[66:67]
	v_add_f32_e32 v5, v5, v65
	v_add_f32_e32 v5, v5, v66
	v_add_f32_e32 v5, v5, v67
	ds_bpermute_b32 v31, v170, v5
	s_waitcnt lgkmcnt(0)
	v_add_f32_e32 v5, v5, v31
	ds_bpermute_b32 v31, v171, v5
	s_waitcnt lgkmcnt(0)
	v_add_f32_e32 v5, v5, v31
	ds_bpermute_b32 v31, v172, v5
	s_waitcnt lgkmcnt(0)
	v_add_f32_e32 v5, v5, v31
	ds_bpermute_b32 v31, v173, v5
	s_waitcnt lgkmcnt(0)
	v_add_f32_e32 v5, v5, v31
	ds_bpermute_b32 v31, v174, v5
	s_waitcnt lgkmcnt(0)
	v_add_f32_e32 v5, v5, v31
	ds_bpermute_b32 v31, v175, v5
	s_waitcnt lgkmcnt(0)
	v_add_f32_e32 v5, v5, v31
	v_fmamk_f32 v5, v5, 0x3a000000, v30
	v_mul_f32_e32 v31, 0x4b800000, v5
	v_cmp_gt_f32_e32 vcc, s5, v5
	s_nop 1
	v_cndmask_b32_e32 v5, v5, v31, vcc
	v_rsq_f32_e32 v5, v5
	s_nop 0
	v_mul_f32_e32 v31, 0x45800000, v5
	v_cndmask_b32_e32 v64, v5, v31, vcc
	v_add_co_u32_e32 v120, vcc, s4, v28
	s_nop 1
	v_addc_co_u32_e32 v121, vcc, 0, v29, vcc
	v_cmp_lt_i32_e32 vcc, s6, v4
	s_or_b64 s[0:1], vcc, s[0:1]
	v_pk_mul_f32 v[32:33], v[32:33], v[64:65] op_sel_hi:[1,0]
	v_pk_mul_f32 v[34:35], v[34:35], v[64:65] op_sel_hi:[1,0]
	v_pk_mul_f32 v[32:33], v[88:89], v[32:33]
	v_pk_mul_f32 v[34:35], v[90:91], v[34:35]
	global_store_dwordx4 v[28:29], v[32:35], off
	v_pk_mul_f32 v[36:37], v[36:37], v[64:65] op_sel_hi:[1,0]
	v_pk_mul_f32 v[38:39], v[38:39], v[64:65] op_sel_hi:[1,0]
	v_pk_mul_f32 v[36:37], v[92:93], v[36:37]
	v_pk_mul_f32 v[38:39], v[94:95], v[38:39]
	global_store_dwordx4 v[28:29], v[36:39], off offset:1024
	v_pk_mul_f32 v[40:41], v[40:41], v[64:65] op_sel_hi:[1,0]
	v_pk_mul_f32 v[42:43], v[42:43], v[64:65] op_sel_hi:[1,0]
	v_pk_mul_f32 v[40:41], v[96:97], v[40:41]
	v_pk_mul_f32 v[42:43], v[98:99], v[42:43]
	global_store_dwordx4 v[28:29], v[40:43], off offset:2048
	v_pk_mul_f32 v[44:45], v[44:45], v[64:65] op_sel_hi:[1,0]
	v_pk_mul_f32 v[46:47], v[46:47], v[64:65] op_sel_hi:[1,0]
	v_pk_mul_f32 v[44:45], v[100:101], v[44:45]
	v_pk_mul_f32 v[46:47], v[102:103], v[46:47]
	global_store_dwordx4 v[28:29], v[44:47], off offset:3072
	v_pk_mul_f32 v[48:49], v[48:49], v[64:65] op_sel_hi:[1,0]
	v_pk_mul_f32 v[50:51], v[50:51], v[64:65] op_sel_hi:[1,0]
	v_pk_mul_f32 v[48:49], v[104:105], v[48:49]
	v_pk_mul_f32 v[50:51], v[106:107], v[50:51]
	global_store_dwordx4 v[120:121], v[48:51], off
	v_pk_mul_f32 v[52:53], v[52:53], v[64:65] op_sel_hi:[1,0]
	v_pk_mul_f32 v[54:55], v[54:55], v[64:65] op_sel_hi:[1,0]
	v_pk_mul_f32 v[52:53], v[108:109], v[52:53]
	v_pk_mul_f32 v[54:55], v[110:111], v[54:55]
	global_store_dwordx4 v[120:121], v[52:55], off offset:1024
	v_pk_mul_f32 v[56:57], v[56:57], v[64:65] op_sel_hi:[1,0]
	v_pk_mul_f32 v[58:59], v[58:59], v[64:65] op_sel_hi:[1,0]
	v_pk_mul_f32 v[56:57], v[112:113], v[56:57]
	v_pk_mul_f32 v[58:59], v[114:115], v[58:59]
	global_store_dwordx4 v[120:121], v[56:59], off offset:2048
	v_pk_mul_f32 v[0:1], v[0:1], v[64:65] op_sel_hi:[1,0]
	v_pk_mul_f32 v[2:3], v[2:3], v[64:65] op_sel_hi:[1,0]
	v_pk_mul_f32 v[0:1], v[116:117], v[0:1]
	v_pk_mul_f32 v[2:3], v[118:119], v[2:3]
	global_store_dwordx4 v[120:121], v[0:3], off offset:3072
	s_andn2_b64 exec, exec, s[0:1]
	s_cbranch_execnz .LBB0_1367
